# DSA_IN: last k-iteration L2-prefetches next tile's first two A k-tiles via LDS-DMA dword into unused LDS scratch (hides tile-prologue miss latency)
# speedup vs baseline: 1.0023x; 1.0023x over previous
; #define MFMA(a, b, c) __builtin_amdgcn_mfma_f32_32x32x16_bf16((a), (b), (c), 0, 0, 0)
; DI void gt_compute(const bf16* asr, const bf16* bsr, f32x16& acc0, f32x16& acc1, f32x16& acc2, f32x16& acc3) {
;   bf16x8 a[4], b0[4], b1[4], b2[4], b3[4];
; #pragma unroll
;   for (int kk = 0; kk < 4; ++kk) {
;     a[kk] = *(const bf16x8*)(asr + kk * 16);
;     b0[kk] = *(const bf16x8*)(bsr + kk * 16);
;     b1[kk] = *(const bf16x8*)(bsr + 32 * LDT + kk * 16);
;     b2[kk] = *(const bf16x8*)(bsr + 64 * LDT + kk * 16);
;     b3[kk] = *(const bf16x8*)(bsr + 96 * LDT + kk * 16);
;   }
;   __builtin_amdgcn_sched_barrier(0);
;   __builtin_amdgcn_s_setprio(2);
; #pragma unroll
;   for (int kk = 0; kk < 4; ++kk) {
;     acc0 = MFMA(a[kk], b0[kk], acc0); acc1 = MFMA(a[kk], b1[kk], acc1); acc2 = MFMA(a[kk], b2[kk], acc2); acc3 = MFMA(a[kk], b3[kk], acc3);
;   }
;   __builtin_amdgcn_s_setprio(0);
;   __builtin_amdgcn_sched_barrier(0);
; DI void gemm_mainloop(const bf16* __restrict__ A, int lda, const bf16* __restrict__ Bt, int ldb, int K, int m0, int n0,
;                       bf16* As, bf16* Bs, f32x16& acc0, f32x16& acc1, f32x16& acc2, f32x16& acc3) {
;     ...
;   int kb = ((((m0 >> 7) * 5 + (n0 >> 7) * 3) >> 1) % nkt) << 6;
;     ...
;   gt_load(t0, ap, bp, lda, ldb, KW(0));
;   gt_load(t1, ap, bp, lda, ldb, KW(64));
; #pragma unroll
;   for (int i = 0; i < 16; ++i) { acc0[i] = 0.f; acc1[i] = 0.f; acc2[i] = 0.f; acc3[i] = 0.f; }
;   bf16* asw = As + lrow * LDT + lcc;
;   bf16* bsw = Bs + lrow * LDT + lcc;
;   const bf16* asr = As + (32 * w + r) * LDT + g * 8;
;   const bf16* bsr = Bs + r * LDT + g * 8;
;   for (int k0 = 0; k0 < K; k0 += 128) {
;     __syncthreads();
;     gt_store(t0, asw, bsw);
;     __syncthreads();
;     if (k0 + 128 < K) gt_load(t0, ap, bp, lda, ldb, KW(k0 + 128));
;     gt_compute(asr, bsr, acc0, acc1, acc2, acc3);
;     __syncthreads();
;     gt_store(t1, asw, bsw);
;     __syncthreads();
;     if (k0 + 192 < K) gt_load(t1, ap, bp, lda, ldb, KW(k0 + 192));
;     gt_compute(asr, bsr, acc0, acc1, acc2, acc3);
.LBB0_953:
	s_add_i32 s98, s53, s54
	s_cmp_lt_i32 s98, s55
	s_cselect_b32 s98, s98, s53
	s_cmp_eq_u32 s56, 0
	s_cselect_b32 s98, 0, s98
	s_movk_i32 s99, 0x4000
	s_cmp_eq_u32 s56, 3
	s_cselect_b32 s99, 0x5556, s99
	s_mul_i32 s99, s98, s99
	s_lshr_b32 s99, s99, 16
	s_mul_i32 s100, s99, s56
	s_sub_i32 s100, s98, s100
	s_lshl_b32 s100, s100, 3
	s_add_i32 s100, s100, s52
	s_mul_i32 s101, s99, 5
	s_mul_i32 s100, s100, 3
	s_add_i32 s101, s101, s100
	s_lshr_b32 s101, s101, 1
	s_and_b32 s101, s101, 15
	s_lshl_b32 s101, s101, 6
	s_lshl_b32 s99, s99, 18
	s_mov_b32 m0, 0xc000
	v_and_b32_e32 v65, 1, v160
	v_lshrrev_b32_e32 v64, 1, v160
	v_lshl_add_u32 v65, v65, 6, s101
	v_lshlrev_b32_e32 v64, 11, v64
	v_and_b32_e32 v65, 0x3ff, v65
	v_add_u32_e32 v64, s99, v64
	v_lshl_add_u32 v64, v65, 1, v64
	global_load_lds_dword v64, s[38:39]
	ds_read_b128 v[174:177], v152
	ds_read_b128 v[178:181], v152 offset:32
	ds_read_b128 v[182:185], v130 offset:18432
	ds_read_b128 v[186:189], v130 offset:18464
	ds_read_b128 v[190:193], v130 offset:23040
	ds_read_b128 v[194:197], v130 offset:23072
	ds_read_b128 v[198:201], v130 offset:27648
	ds_read_b128 v[202:205], v130 offset:27680
	ds_read_b128 v[206:209], v130 offset:32256
	ds_read_b128 v[210:213], v130 offset:32288
	ds_read_b128 v[214:217], v152 offset:64
	ds_read_b128 v[226:229], v152 offset:96
	ds_read_b128 v[230:233], v130 offset:18496
	ds_read_b128 v[234:237], v130 offset:18528
	ds_read_b128 v[238:241], v130 offset:23104
	ds_read_b128 v[242:245], v130 offset:23136
	ds_read_b128 v[246:249], v130 offset:27712
	ds_read_b128 v[250:253], v130 offset:27744
	ds_read_b128 v[156:159], v130 offset:32320
	ds_read_b128 v[162:165], v130 offset:32352
	s_setprio 2
	s_waitcnt lgkmcnt(14)
	v_mfma_f32_32x32x16_bf16 v[48:63], v[174:177], v[182:185], v[48:63]
	v_mfma_f32_32x32x16_bf16 v[16:31], v[174:177], v[190:193], v[16:31]
	s_waitcnt lgkmcnt(13)
	v_mfma_f32_32x32x16_bf16 v[32:47], v[174:177], v[198:201], v[32:47]
	s_waitcnt lgkmcnt(11)
	v_mfma_f32_32x32x16_bf16 v[0:15], v[174:177], v[206:209], v[0:15]
	v_mfma_f32_32x32x16_bf16 v[48:63], v[178:181], v[186:189], v[48:63]
	v_mfma_f32_32x32x16_bf16 v[16:31], v[178:181], v[194:197], v[16:31]
	v_mfma_f32_32x32x16_bf16 v[32:47], v[178:181], v[202:205], v[32:47]
	s_waitcnt lgkmcnt(10)
	v_mfma_f32_32x32x16_bf16 v[0:15], v[178:181], v[210:213], v[0:15]
	s_waitcnt lgkmcnt(7)
	v_mfma_f32_32x32x16_bf16 v[48:63], v[214:217], v[230:233], v[48:63]
	s_waitcnt lgkmcnt(5)
	v_mfma_f32_32x32x16_bf16 v[16:31], v[214:217], v[238:241], v[16:31]
	s_waitcnt lgkmcnt(3)
	v_mfma_f32_32x32x16_bf16 v[32:47], v[214:217], v[246:249], v[32:47]
	s_waitcnt lgkmcnt(1)
	v_mfma_f32_32x32x16_bf16 v[0:15], v[214:217], v[156:159], v[0:15]
	v_mfma_f32_32x32x16_bf16 v[48:63], v[226:229], v[234:237], v[48:63]
	v_mfma_f32_32x32x16_bf16 v[16:31], v[226:229], v[242:245], v[16:31]
	v_mfma_f32_32x32x16_bf16 v[32:47], v[226:229], v[250:253], v[32:47]
	s_waitcnt lgkmcnt(0)
	v_mfma_f32_32x32x16_bf16 v[0:15], v[226:229], v[162:165], v[0:15]
	s_setprio 0
	s_cmpk_gt_u32 s48, 0x33f
	s_barrier
	s_waitcnt vmcnt(6)
	ds_write_b128 v150, v[100:103]
	ds_write_b128 v150, v[88:91] offset:4608
	ds_write_b128 v150, v[92:95] offset:9216
	s_waitcnt vmcnt(4)
	ds_write_b128 v150, v[112:115] offset:13824
	ds_write_b128 v150, v[108:111] offset:18432
	s_waitcnt vmcnt(3)
	ds_write_b128 v150, v[116:119] offset:23040
	s_waitcnt vmcnt(2)
	ds_write_b128 v150, v[120:123] offset:27648
	s_waitcnt vmcnt(1)
	ds_write_b128 v150, v[124:127] offset:32256
	s_waitcnt lgkmcnt(0)
	s_barrier
	s_cbranch_scc1 .LBB0_950
